# v29: v27 + phase-0 adaLN GEMV weight-row loads software-prefetched one k16 iteration ahead (spare VGPRs)
# baseline (speedup 1.0000x reference)
.LBB0_10:
	v_add_u32_e32 v0, s40, v4
	v_add_u32_e32 v22, s40, v12
	v_add_u32_e32 v19, -16, v0
	v_cmp_gt_u32_e64 s[4:5], s41, v17
	v_add_u32_e32 v24, s40, v11
	v_add_u32_e32 v18, 0x1000, v17
	v_add_u32_e32 v23, -16, v22
	v_cmp_gt_u32_e64 s[6:7], s42, v17
	v_cndmask_b32_e64 v0, v19, v0, s[4:5]
	v_add_u32_e32 v26, s40, v10
	v_cmp_lt_u32_e32 vcc, s49, v17
	v_add_u32_e32 v25, -16, v24
	v_cmp_gt_u32_e64 s[8:9], s43, v17
	v_cmp_gt_u32_e64 s[10:11], s44, v17
	v_cmp_gt_u32_e64 s[12:13], s45, v17
	v_cmp_gt_u32_e64 s[14:15], s46, v17
	v_cmp_gt_u32_e64 s[18:19], s47, v17
	v_cmp_gt_u32_e64 s[20:21], s48, v17
	v_mov_b32_e32 v17, v18
	v_cndmask_b32_e64 v19, v13, v14, s[4:5]
	v_cndmask_b32_e64 v18, v15, v16, s[4:5]
	v_lshlrev_b64 v[20:21], 12, v[0:1]
	v_cndmask_b32_e64 v0, v23, v22, s[6:7]
	v_add_u32_e32 v28, s40, v9
	v_add_u32_e32 v27, -16, v26
	v_cndmask_b32_e64 v23, v13, v14, s[6:7]
	v_cndmask_b32_e64 v22, v15, v16, s[6:7]
	v_lshl_add_u64 v[18:19], v[18:19], 0, v[20:21]
	v_lshlrev_b64 v[20:21], 12, v[0:1]
	v_cndmask_b32_e64 v0, v25, v24, s[8:9]
	v_add_u32_e32 v29, s40, v8
	v_add_u32_e32 v32, -16, v28
	v_cndmask_b32_e64 v25, v13, v14, s[8:9]
	v_cndmask_b32_e64 v24, v15, v16, s[8:9]
	v_lshl_add_u64 v[18:19], v[18:19], 0, v[2:3]
	v_lshl_add_u64 v[20:21], v[22:23], 0, v[20:21]
	v_lshlrev_b64 v[22:23], 12, v[0:1]
	v_cndmask_b32_e64 v0, v27, v26, s[10:11]
	v_add_u32_e32 v30, s40, v7
	v_add_u32_e32 v33, -16, v29
	v_cndmask_b32_e64 v27, v13, v14, s[10:11]
	v_cndmask_b32_e64 v26, v15, v16, s[10:11]
	global_load_dword v36, v[18:19], off
	v_lshl_add_u64 v[18:19], v[20:21], 0, v[2:3]
	v_lshl_add_u64 v[20:21], v[24:25], 0, v[22:23]
	v_lshlrev_b64 v[22:23], 12, v[0:1]
	v_cndmask_b32_e64 v0, v32, v28, s[12:13]
	v_add_u32_e32 v31, s40, v6
	v_add_u32_e32 v34, -16, v30
	v_cndmask_b32_e64 v25, v13, v14, s[12:13]
	v_cndmask_b32_e64 v24, v15, v16, s[12:13]
	global_load_dword v28, v[18:19], off offset:2048
	v_lshl_add_u64 v[18:19], v[20:21], 0, v[2:3]
	v_lshl_add_u64 v[20:21], v[26:27], 0, v[22:23]
	v_lshlrev_b64 v[22:23], 12, v[0:1]
	v_cndmask_b32_e64 v0, v33, v29, s[14:15]
	v_add_u32_e32 v35, -16, v31
	v_cndmask_b32_e64 v27, v13, v14, s[14:15]
	v_cndmask_b32_e64 v26, v15, v16, s[14:15]
	global_load_dword v29, v[18:19], off
	v_lshl_add_u64 v[18:19], v[20:21], 0, v[2:3]
	v_lshl_add_u64 v[20:21], v[24:25], 0, v[22:23]
	v_lshlrev_b64 v[22:23], 12, v[0:1]
	v_cndmask_b32_e64 v0, v34, v30, s[18:19]
	v_cndmask_b32_e64 v25, v13, v14, s[18:19]
	v_cndmask_b32_e64 v24, v15, v16, s[18:19]
	global_load_dword v30, v[18:19], off offset:2048
	v_lshl_add_u64 v[18:19], v[20:21], 0, v[2:3]
	v_lshl_add_u64 v[20:21], v[26:27], 0, v[22:23]
	v_lshlrev_b64 v[22:23], 12, v[0:1]
	v_cndmask_b32_e64 v0, v35, v31, s[20:21]
	v_cndmask_b32_e64 v27, v13, v14, s[20:21]
	v_cndmask_b32_e64 v26, v15, v16, s[20:21]
	global_load_dword v31, v[18:19], off
	v_lshl_add_u64 v[18:19], v[20:21], 0, v[2:3]
	v_lshl_add_u64 v[20:21], v[24:25], 0, v[22:23]
	v_lshlrev_b64 v[22:23], 12, v[0:1]
	global_load_dword v0, v[18:19], off offset:2048
	v_lshl_add_u64 v[18:19], v[20:21], 0, v[2:3]
	v_lshl_add_u64 v[20:21], v[26:27], 0, v[22:23]
	global_load_dword v22, v[18:19], off
	v_lshl_add_u64 v[18:19], v[20:21], 0, v[2:3]
	global_load_dword v18, v[18:19], off offset:2048
	s_add_i32 s40, s40, 4
	s_or_b64 s[38:39], vcc, s[38:39]
	s_waitcnt vmcnt(7)
	v_mul_f32_e32 v19, 0xbfb8aa3b, v36
	v_exp_f32_e32 v19, v19
	s_waitcnt vmcnt(6)
	v_mul_f32_e32 v20, 0xbfb8aa3b, v28
	v_exp_f32_e32 v20, v20
	v_add_f32_e32 v19, 1.0, v19
	v_div_scale_f32 v26, s[4:5], v19, v19, v36
	v_add_f32_e32 v20, 1.0, v20
	v_rcp_f32_e32 v33, v26
	v_div_scale_f32 v34, s[4:5], v20, v20, v28
	s_waitcnt vmcnt(5)
	v_mul_f32_e32 v21, 0xbfb8aa3b, v29
	v_exp_f32_e32 v21, v21
	v_rcp_f32_e32 v38, v34
	v_fma_f32 v47, -v26, v33, 1.0
	v_div_scale_f32 v27, vcc, v36, v19, v36
	s_waitcnt vmcnt(4)
	v_mul_f32_e32 v23, 0xbfb8aa3b, v30
	v_exp_f32_e32 v23, v23
	v_add_f32_e32 v21, 1.0, v21
	v_div_scale_f32 v39, s[6:7], v21, v21, v29
	v_add_f32_e32 v23, 1.0, v23
	v_rcp_f32_e32 v41, v39
	s_waitcnt vmcnt(3)
	v_mul_f32_e32 v24, 0xbfb8aa3b, v31
	v_exp_f32_e32 v24, v24
	v_div_scale_f32 v42, s[8:9], v23, v23, v30
	s_waitcnt vmcnt(2)
	v_mul_f32_e32 v25, 0xbfb8aa3b, v0
	v_exp_f32_e32 v25, v25
	v_add_f32_e32 v24, 1.0, v24
	s_waitcnt vmcnt(1)
	v_mul_f32_e32 v32, 0xbfb8aa3b, v22
	v_exp_f32_e32 v32, v32
	s_waitcnt vmcnt(0)
	v_mul_f32_e32 v37, 0xbfb8aa3b, v18
	v_exp_f32_e32 v37, v37
	v_rcp_f32_e32 v44, v42
	v_div_scale_f32 v45, s[10:11], v24, v24, v31
	v_add_f32_e32 v25, 1.0, v25
	v_rcp_f32_e32 v49, v45
	v_div_scale_f32 v50, s[12:13], v25, v25, v0
	v_add_f32_e32 v32, 1.0, v32
	v_fmac_f32_e32 v33, v47, v33
	v_fma_f32 v47, -v34, v38, 1.0
	v_rcp_f32_e32 v52, v50
	v_div_scale_f32 v53, s[14:15], v32, v32, v22
	v_add_f32_e32 v37, 1.0, v37
	v_div_scale_f32 v35, s[4:5], v28, v20, v28
	v_mul_f32_e32 v55, v27, v33
	v_fmac_f32_e32 v38, v47, v38
	v_fma_f32 v47, -v39, v41, 1.0
	v_rcp_f32_e32 v56, v53
	v_div_scale_f32 v57, s[18:19], v37, v37, v18
	v_div_scale_f32 v40, s[6:7], v29, v21, v29
	v_fma_f32 v59, -v26, v55, v27
	v_fmac_f32_e32 v41, v47, v41
	v_mul_f32_e32 v47, v35, v38
	v_fma_f32 v60, -v42, v44, 1.0
	v_rcp_f32_e32 v61, v57
	v_div_scale_f32 v43, s[8:9], v30, v23, v30
	v_fmac_f32_e32 v55, v59, v33
	v_fma_f32 v59, -v34, v47, v35
	v_mul_f32_e32 v62, v40, v41
	v_fmac_f32_e32 v44, v60, v44
	v_fma_f32 v60, -v45, v49, 1.0
	v_div_scale_f32 v46, s[10:11], v31, v24, v31
	v_fma_f32 v26, -v26, v55, v27
	v_fmac_f32_e32 v47, v59, v38
	v_fma_f32 v27, -v39, v62, v40
	v_fmac_f32_e32 v49, v60, v49
	v_mul_f32_e32 v59, v43, v44
	v_fma_f32 v60, -v50, v52, 1.0
	v_div_scale_f32 v51, s[12:13], v0, v25, v0
	v_div_fmas_f32 v26, v26, v33, v55
	v_fma_f32 v33, -v34, v47, v35
	v_fmac_f32_e32 v62, v27, v41
	v_fma_f32 v27, -v42, v59, v43
	v_fmac_f32_e32 v52, v60, v52
	v_mul_f32_e32 v34, v46, v49
	v_fma_f32 v35, -v53, v56, 1.0
	s_mov_b64 vcc, s[4:5]
	v_div_scale_f32 v54, s[14:15], v22, v32, v22
	v_div_fixup_f32 v19, v26, v19, v36
	v_div_fmas_f32 v26, v33, v38, v47
	v_fma_f32 v33, -v39, v62, v40
	v_fmac_f32_e32 v59, v27, v44
	v_fma_f32 v27, -v45, v34, v46
	v_mul_f32_e32 v36, v51, v52
	v_fmac_f32_e32 v56, v35, v56
	v_fma_f32 v35, -v57, v61, 1.0
	s_mov_b64 vcc, s[6:7]
	v_div_scale_f32 v58, s[18:19], v18, v37, v18
	v_div_fixup_f32 v20, v26, v20, v28
	v_div_fmas_f32 v26, v33, v41, v62
	v_fma_f32 v28, -v42, v59, v43
	v_fmac_f32_e32 v34, v27, v49
	v_fma_f32 v27, -v50, v36, v51
	v_mul_f32_e32 v33, v54, v56
	v_fmac_f32_e32 v61, v35, v61
	s_mov_b64 vcc, s[8:9]
	ds_write2st64_b32 v5, v19, v20 offset1:8
	v_div_fixup_f32 v19, v26, v21, v29
	v_div_fmas_f32 v20, v28, v44, v59
	v_fma_f32 v21, -v45, v34, v46
	v_fmac_f32_e32 v36, v27, v52
	v_fma_f32 v26, -v53, v33, v54
	v_mul_f32_e32 v27, v58, v61
	s_mov_b64 vcc, s[10:11]
	v_div_fixup_f32 v20, v20, v23, v30
	v_div_fmas_f32 v21, v21, v49, v34
	v_fma_f32 v23, -v50, v36, v51
	v_fmac_f32_e32 v33, v26, v56
	v_fma_f32 v26, -v57, v27, v58
	s_mov_b64 vcc, s[12:13]
	ds_write2st64_b32 v5, v19, v20 offset0:16 offset1:24
	v_div_fixup_f32 v19, v21, v24, v31
	v_div_fmas_f32 v20, v23, v52, v36
	v_fma_f32 v21, -v53, v33, v54
	v_fmac_f32_e32 v27, v26, v61
	s_mov_b64 vcc, s[14:15]
	v_div_fixup_f32 v0, v20, v25, v0
	v_div_fmas_f32 v20, v21, v56, v33
	v_fma_f32 v21, -v57, v27, v58
	s_mov_b64 vcc, s[18:19]
	ds_write2st64_b32 v5, v19, v0 offset0:32 offset1:40
	v_div_fmas_f32 v19, v21, v61, v27
	v_div_fixup_f32 v0, v20, v32, v22
	v_div_fixup_f32 v18, v19, v37, v18
	ds_write2st64_b32 v5, v0, v18 offset0:48 offset1:56
	v_add_u32_e32 v5, 0x4000, v5
	s_andn2_b64 exec, exec, s[38:39]
	s_cbranch_execnz .LBB0_10
	s_or_b64 exec, exec, s[38:39]
	s_mul_hi_i32 s4, s2, 0x2aaaaaab
	s_lshr_b32 s5, s4, 31
	s_ashr_i32 s4, s4, 4
	s_add_i32 s10, s4, s5
	s_mul_i32 s4, s10, 0x60
	s_sub_i32 s4, s2, s4
	s_lshl_b32 s4, s4, 6
	s_lshl_b32 s13, s3, 7
	s_mul_i32 s7, s10, 0x1800000
	s_ashr_i32 s5, s4, 31
	s_or_b32 s11, s13, 0x70
	s_mul_i32 s8, s3, 0x300000
	s_mul_hi_i32 s6, s10, 0x1800000
	s_mul_hi_u32 s9, s13, 0x6000
	s_add_u32 s8, s7, s8
	s_addc_u32 s9, s6, s9
	s_lshl_b64 s[6:7], s[4:5], 2
	s_add_u32 s5, s8, s6
	s_addc_u32 s9, s9, s7
	v_and_b32_e32 v49, 63, v48
	s_add_u32 s8, s28, s5
	v_lshlrev_b32_e32 v50, 2, v49
	v_mov_b32_e32 v51, 0
	s_addc_u32 s9, s29, s9
	v_lshl_add_u64 v[52:53], s[8:9], 0, v[50:51]
	s_lshl_b32 s8, s3, 9
	s_add_i32 s8, s8, 0
	s_movk_i32 s12, 0x6000
	s_add_i32 s5, s13, -16
	s_add_i32 s13, s8, 0x10000
	s_mov_b32 s14, 0xc000
	s_mov_b32 s15, 0x12000
	s_mov_b32 s18, 0x18000
	s_mov_b32 s19, 0x1e000
	s_mov_b32 s20, 0x24000
	s_mov_b32 s21, 0x2a000
	s_mov_b32 s28, 0x30000
	s_mov_b32 s29, 0x36000
	s_mov_b32 s38, 0x3c000
	s_mov_b32 s39, 0x42000
	s_mov_b32 s40, 0x48000
	s_mov_b32 s41, 0x4e000
	s_mov_b32 s42, 0x54000
	s_mov_b32 s43, 0x5a000
	s_mov_b64 s[8:9], 0x60000
	v_mov_b32_e32 v54, v51
	v_mov_b32_e32 v55, v51
	v_mov_b32_e32 v56, v51
	v_mov_b32_e32 v57, v51
	v_mov_b32_e32 v58, v51
	v_mov_b32_e32 v59, v51
	v_mov_b32_e32 v60, v51
	v_mov_b32_e32 v61, v51
	v_mov_b32_e32 v62, v51
	v_mov_b32_e32 v63, v51
	v_mov_b32_e32 v64, v51
	v_mov_b32_e32 v65, v51
	v_mov_b32_e32 v66, v51
	v_mov_b32_e32 v67, v51
	v_mov_b32_e32 v68, v51
	v_mov_b32_e32 v69, v51
	v_mov_b32_e32 v70, v51
	v_mov_b32_e32 v71, v51
	v_mov_b32_e32 v72, v51
	v_mov_b32_e32 v73, v51
	v_mov_b32_e32 v74, v51
	v_mov_b32_e32 v75, v51
	v_mov_b32_e32 v76, v51
	v_mov_b32_e32 v77, v51
	s_waitcnt lgkmcnt(0)
	s_barrier
	s_mov_b32 s100, 0x6000
	s_mov_b32 s101, 0
	global_load_dword v236, v[52:53], off
	v_lshl_add_u64 v[230:231], v[52:53], 0, s[100:101]
	global_load_dword v237, v[230:231], off
	v_lshl_add_u64 v[232:233], v[230:231], 0, s[100:101]
	global_load_dword v238, v[232:233], off
	v_lshl_add_u64 v[228:229], v[232:233], 0, s[100:101]
	global_load_dword v239, v[228:229], off
	v_lshl_add_u64 v[230:231], v[228:229], 0, s[100:101]
	global_load_dword v240, v[230:231], off
	v_lshl_add_u64 v[232:233], v[230:231], 0, s[100:101]
	global_load_dword v241, v[232:233], off
	v_lshl_add_u64 v[228:229], v[232:233], 0, s[100:101]
	global_load_dword v242, v[228:229], off
	v_lshl_add_u64 v[230:231], v[228:229], 0, s[100:101]
	global_load_dword v243, v[230:231], off
	v_lshl_add_u64 v[234:235], v[230:231], 0, s[100:101]
	global_load_dword v244, v[234:235], off
	v_lshl_add_u64 v[228:229], v[234:235], 0, s[100:101]
	global_load_dword v245, v[228:229], off
	v_lshl_add_u64 v[230:231], v[228:229], 0, s[100:101]
	global_load_dword v246, v[230:231], off
	v_lshl_add_u64 v[232:233], v[230:231], 0, s[100:101]
	global_load_dword v247, v[232:233], off
	v_lshl_add_u64 v[228:229], v[232:233], 0, s[100:101]
	global_load_dword v248, v[228:229], off
	v_lshl_add_u64 v[230:231], v[228:229], 0, s[100:101]
	global_load_dword v249, v[230:231], off
	v_lshl_add_u64 v[232:233], v[230:231], 0, s[100:101]
	global_load_dword v250, v[232:233], off
	v_lshl_add_u64 v[228:229], v[232:233], 0, s[100:101]
	global_load_dword v251, v[228:229], off
.LBB0_12:
	v_mov_b32_e32 v127, s13
	ds_read_b128 v[24:27], v127
	ds_read_b128 v[0:3], v127 offset:16
	ds_read_b128 v[8:11], v127 offset:4096
	ds_read_b128 v[12:15], v127 offset:12288
	ds_read_b128 v[16:19], v127 offset:4112
	ds_read_b128 v[32:35], v127 offset:8192
	ds_read_b128 v[4:7], v127 offset:8208
	s_waitcnt lgkmcnt(4)
	v_mov_b32_e32 v82, v8
	v_mov_b32_e32 v83, v24
	v_mov_b32_e32 v24, v9
	v_mov_b32_e32 v78, v10
	v_mov_b32_e32 v79, v26
	v_mov_b32_e32 v26, v11
	ds_read_b128 v[20:23], v127 offset:12304
	s_waitcnt lgkmcnt(4)
	v_mov_b32_e32 v86, v12
	s_waitcnt lgkmcnt(2)
	v_mov_b32_e32 v87, v32
	v_mov_b32_e32 v32, v13
	v_mov_b32_e32 v80, v14
	v_mov_b32_e32 v81, v34
	v_mov_b32_e32 v34, v15
	ds_read_b128 v[12:15], v127 offset:20480
	ds_read_b128 v[28:31], v127 offset:20496
	ds_read_b128 v[40:43], v127 offset:16384
	ds_read_b128 v[8:11], v127 offset:16400
	ds_read_b128 v[94:97], v127 offset:28672
	ds_read_b128 v[36:39], v127 offset:28688
	s_add_i32 s45, s13, 0xffff1000
	s_waitcnt lgkmcnt(5)
	v_mov_b32_e32 v88, v12
	s_waitcnt lgkmcnt(3)
	v_mov_b32_e32 v89, v40
	v_mov_b32_e32 v40, v13
	v_mov_b32_e32 v84, v14
	v_mov_b32_e32 v85, v42
	v_mov_b32_e32 v42, v15
	ds_read_b128 v[44:47], v127 offset:24576
	ds_read_b128 v[12:15], v127 offset:24592
	s_waitcnt lgkmcnt(3)
	v_mov_b32_e32 v92, v94
	s_add_i32 s44, s13, 0xffff0000
	v_mov_b32_e32 v94, s45
	s_waitcnt lgkmcnt(1)
	v_mov_b32_e32 v93, v44
	v_mov_b32_e32 v44, v95
	v_mov_b32_e32 v90, v96
	v_mov_b32_e32 v91, v46
	v_mov_b32_e32 v46, v97
	v_mov_b32_e32 v98, s44
	ds_read_b128 v[94:97], v94
	ds_read_b128 v[98:101], v98
	s_add_i32 s45, s13, 0xffff3000
	s_add_i32 s44, s13, 0xffff2000
	v_mov_b32_e32 v102, s44
	s_waitcnt lgkmcnt(1)
	v_mov_b32_e32 v140, v94
	v_mov_b32_e32 v94, s45
	s_waitcnt lgkmcnt(0)
	v_mov_b32_e32 v141, v98
	v_mov_b32_e32 v98, v95
	v_mov_b32_e32 v142, v96
	v_mov_b32_e32 v143, v100
	v_mov_b32_e32 v100, v97
	ds_read_b128 v[94:97], v94
	ds_read_b128 v[108:111], v102
	s_add_i32 s45, s13, 0xffff5000
	s_add_i32 s44, s13, 0xffff4000
	v_mov_b32_e32 v102, s44
	s_waitcnt lgkmcnt(1)
	v_mov_b32_e32 v144, v94
	v_mov_b32_e32 v94, s45
	s_waitcnt lgkmcnt(0)
	v_mov_b32_e32 v145, v108
	v_mov_b32_e32 v108, v95
	v_mov_b32_e32 v146, v96
	v_mov_b32_e32 v147, v110
	v_mov_b32_e32 v110, v97
	ds_read_b128 v[94:97], v94
	ds_read_b128 v[112:115], v102
	s_add_i32 s45, s13, 0xffff7000
	s_add_i32 s44, s13, 0xffff6000
	v_mov_b32_e32 v102, s44
	s_waitcnt lgkmcnt(1)
	v_mov_b32_e32 v148, v94
	v_mov_b32_e32 v94, s45
	s_waitcnt lgkmcnt(0)
	v_mov_b32_e32 v149, v112
	v_mov_b32_e32 v112, v95
	v_mov_b32_e32 v150, v96
	v_mov_b32_e32 v151, v114
	v_mov_b32_e32 v114, v97
	ds_read_b128 v[94:97], v94
	ds_read_b128 v[116:119], v102
	s_add_i32 s45, s13, 0xffff9000
	s_add_i32 s44, s13, 0xffff8000
	v_mov_b32_e32 v102, s44
	s_waitcnt lgkmcnt(1)
	v_mov_b32_e32 v152, v94
	v_mov_b32_e32 v94, s45
	s_waitcnt lgkmcnt(0)
	v_mov_b32_e32 v153, v116
	v_mov_b32_e32 v116, v95
	v_mov_b32_e32 v154, v96
	v_mov_b32_e32 v155, v118
	v_mov_b32_e32 v118, v97
	ds_read_b128 v[94:97], v94
	ds_read_b128 v[120:123], v102
	s_add_i32 s45, s13, 0xffffb000
	s_add_i32 s44, s13, 0xffffa000
	v_mov_b32_e32 v102, s44
	s_waitcnt lgkmcnt(1)
	v_mov_b32_e32 v156, v94
	v_mov_b32_e32 v94, s45
	s_waitcnt lgkmcnt(0)
	v_mov_b32_e32 v157, v120
	v_mov_b32_e32 v120, v95
	v_mov_b32_e32 v158, v96
	v_mov_b32_e32 v159, v122
	v_mov_b32_e32 v122, v97
	ds_read_b128 v[94:97], v94
	ds_read_b128 v[128:131], v102
	s_add_i32 s45, s13, 0xffffd000
	s_add_i32 s44, s13, 0xffffc000
	v_mov_b32_e32 v102, s44
	s_waitcnt lgkmcnt(1)
	v_mov_b32_e32 v160, v94
	v_mov_b32_e32 v94, s45
	s_waitcnt lgkmcnt(0)
	v_mov_b32_e32 v161, v128
	v_mov_b32_e32 v128, v95
	v_mov_b32_e32 v162, v96
	v_mov_b32_e32 v163, v130
	v_mov_b32_e32 v130, v97
	ds_read_b128 v[94:97], v94
	ds_read_b128 v[132:135], v102
	s_add_i32 s45, s13, 0xfffff000
	s_add_i32 s44, s13, 0xffffe000
	v_mov_b32_e32 v102, s44
	s_waitcnt lgkmcnt(1)
	v_mov_b32_e32 v164, v94
	v_mov_b32_e32 v94, s45
	s_waitcnt lgkmcnt(0)
	v_mov_b32_e32 v165, v132
	v_mov_b32_e32 v132, v95
	v_mov_b32_e32 v166, v96
	v_mov_b32_e32 v167, v134
	v_mov_b32_e32 v134, v97
	ds_read_b128 v[94:97], v94
	ds_read_b128 v[136:139], v102
	s_add_i32 s45, s13, 0xffff1010
	s_add_i32 s44, s13, 0xffff0010
	s_add_i32 s5, s5, 16
	s_waitcnt lgkmcnt(1)
	v_mov_b32_e32 v168, v94
	v_mov_b32_e32 v94, v96
	v_add_co_u32_e32 v96, vcc, s12, v52
	s_waitcnt lgkmcnt(0)
	v_mov_b32_e32 v169, v136
	v_mov_b32_e32 v136, v95
	v_mov_b32_e32 v95, v138
	v_mov_b32_e32 v138, v97
	v_addc_co_u32_e32 v97, vcc, 0, v53, vcc
	v_add_co_u32_e32 v102, vcc, s14, v52
	s_nop 1
	v_addc_co_u32_e32 v103, vcc, 0, v53, vcc
	v_add_co_u32_e32 v104, vcc, s15, v52
	s_nop 1
	v_addc_co_u32_e32 v105, vcc, 0, v53, vcc
	v_add_co_u32_e32 v106, vcc, s18, v52
	s_nop 1
	v_addc_co_u32_e32 v107, vcc, 0, v53, vcc
	v_add_co_u32_e32 v124, vcc, s19, v52
	s_nop 1
	v_addc_co_u32_e32 v125, vcc, 0, v53, vcc
	v_add_co_u32_e32 v170, vcc, s20, v52
	s_nop 1
	v_addc_co_u32_e32 v171, vcc, 0, v53, vcc
	v_add_co_u32_e32 v172, vcc, s21, v52
	s_nop 1
	v_addc_co_u32_e32 v173, vcc, 0, v53, vcc
	v_add_co_u32_e32 v174, vcc, s28, v52
	s_nop 1
	v_addc_co_u32_e32 v175, vcc, 0, v53, vcc
	s_waitcnt vmcnt(7)
	v_mov_b32_e32 v96, v237
	v_mov_b32_e32 v176, v238
	v_mov_b32_e32 v178, v239
	v_mov_b32_e32 v104, v240
	v_mov_b32_e32 v106, v241
	v_mov_b32_e32 v102, v242
	v_mov_b32_e32 v124, v243
	v_mov_b32_e32 v126, v244
	v_mov_b32_e32 v170, v236
	s_cmp_lt_u32 s5, s11
	s_cbranch_scc0 .Lp0_noA
	v_lshl_add_u64 v[228:229], v[52:53], 0, s[8:9]
	global_load_dword v236, v[228:229], off
	v_lshl_add_u64 v[230:231], v[228:229], 0, s[100:101]
	global_load_dword v237, v[230:231], off
	v_lshl_add_u64 v[232:233], v[230:231], 0, s[100:101]
	global_load_dword v238, v[232:233], off
	v_lshl_add_u64 v[228:229], v[232:233], 0, s[100:101]
	global_load_dword v239, v[228:229], off
	v_lshl_add_u64 v[230:231], v[228:229], 0, s[100:101]
	global_load_dword v240, v[230:231], off
	v_lshl_add_u64 v[232:233], v[230:231], 0, s[100:101]
	global_load_dword v241, v[232:233], off
	v_lshl_add_u64 v[228:229], v[232:233], 0, s[100:101]
	global_load_dword v242, v[228:229], off
	v_lshl_add_u64 v[230:231], v[228:229], 0, s[100:101]
	global_load_dword v243, v[230:231], off
	v_lshl_add_u64 v[234:235], v[230:231], 0, s[100:101]
	global_load_dword v244, v[234:235], off
.Lp0_noA:
	v_pk_mul_f32 v[116:117], v[96:97], v[116:117] op_sel_hi:[0,1]
	v_pk_mul_f32 v[136:137], v[96:97], v[136:137] op_sel_hi:[0,1]
	v_pk_mul_f32 v[24:25], v[96:97], v[24:25] op_sel_hi:[0,1]
	v_pk_mul_f32 v[108:109], v[96:97], v[108:109] op_sel_hi:[0,1]
	v_pk_mul_f32 v[120:121], v[96:97], v[120:121] op_sel_hi:[0,1]
	v_pk_mul_f32 v[32:33], v[96:97], v[32:33] op_sel_hi:[0,1]
	v_pk_mul_f32 v[40:41], v[96:97], v[40:41] op_sel_hi:[0,1]
	v_pk_mul_f32 v[44:45], v[96:97], v[44:45] op_sel_hi:[0,1]
	v_pk_fma_f32 v[116:117], v[170:171], v[152:153], v[116:117] op_sel_hi:[0,1,1]
	v_pk_fma_f32 v[136:137], v[170:171], v[168:169], v[136:137] op_sel_hi:[0,1,1]
	v_pk_fma_f32 v[24:25], v[170:171], v[82:83], v[24:25] op_sel_hi:[0,1,1]
	v_pk_mul_f32 v[98:99], v[96:97], v[98:99] op_sel_hi:[0,1]
	v_pk_fma_f32 v[108:109], v[170:171], v[144:145], v[108:109] op_sel_hi:[0,1,1]
	v_pk_mul_f32 v[112:113], v[96:97], v[112:113] op_sel_hi:[0,1]
	v_pk_fma_f32 v[120:121], v[170:171], v[156:157], v[120:121] op_sel_hi:[0,1,1]
	v_pk_mul_f32 v[128:129], v[96:97], v[128:129] op_sel_hi:[0,1]
	v_pk_fma_f32 v[32:33], v[170:171], v[86:87], v[32:33] op_sel_hi:[0,1,1]
	v_pk_fma_f32 v[40:41], v[170:171], v[88:89], v[40:41] op_sel_hi:[0,1,1]
	v_pk_fma_f32 v[44:45], v[170:171], v[92:93], v[44:45] op_sel_hi:[0,1,1]
	v_pk_fma_f32 v[92:93], v[176:177], v[154:155], v[116:117] op_sel_hi:[0,1,1]
	v_pk_fma_f32 v[94:95], v[176:177], v[94:95], v[136:137] op_sel_hi:[0,1,1]
	v_pk_fma_f32 v[24:25], v[176:177], v[78:79], v[24:25] op_sel_hi:[0,1,1]
	v_pk_fma_f32 v[98:99], v[170:171], v[140:141], v[98:99] op_sel_hi:[0,1,1]
	v_pk_fma_f32 v[112:113], v[170:171], v[148:149], v[112:113] op_sel_hi:[0,1,1]
	v_pk_fma_f32 v[128:129], v[170:171], v[160:161], v[128:129] op_sel_hi:[0,1,1]
	v_pk_mul_f32 v[132:133], v[96:97], v[132:133] op_sel_hi:[0,1]
	v_pk_fma_f32 v[86:87], v[176:177], v[146:147], v[108:109] op_sel_hi:[0,1,1]
	v_pk_fma_f32 v[96:97], v[176:177], v[158:159], v[120:121] op_sel_hi:[0,1,1]
	v_pk_fma_f32 v[32:33], v[176:177], v[80:81], v[32:33] op_sel_hi:[0,1,1]
	v_pk_fma_f32 v[40:41], v[176:177], v[84:85], v[40:41] op_sel_hi:[0,1,1]
	v_pk_fma_f32 v[84:85], v[178:179], v[118:119], v[92:93] op_sel_hi:[0,1,1]
	v_pk_fma_f32 v[92:93], v[178:179], v[138:139], v[94:95] op_sel_hi:[0,1,1]
	v_pk_fma_f32 v[94:95], v[178:179], v[26:27], v[24:25] op_sel_hi:[0,1,1]
	v_mov_b32_e32 v26, v20
	v_mov_b32_e32 v20, v30
	v_mov_b32_e32 v30, s45
	v_pk_fma_f32 v[82:83], v[176:177], v[142:143], v[98:99] op_sel_hi:[0,1,1]
	v_pk_fma_f32 v[88:89], v[176:177], v[150:151], v[112:113] op_sel_hi:[0,1,1]
	v_pk_fma_f32 v[98:99], v[176:177], v[162:163], v[128:129] op_sel_hi:[0,1,1]
	v_pk_fma_f32 v[80:81], v[178:179], v[110:111], v[86:87] op_sel_hi:[0,1,1]
	v_pk_fma_f32 v[86:87], v[178:179], v[122:123], v[96:97] op_sel_hi:[0,1,1]
	v_pk_fma_f32 v[96:97], v[178:179], v[34:35], v[32:33] op_sel_hi:[0,1,1]
	v_mov_b32_e32 v27, v4
	v_mov_b32_e32 v4, v21
	v_mov_b32_e32 v32, v28
	v_mov_b32_e32 v33, v8
	v_mov_b32_e32 v8, v29
	v_mov_b32_e32 v21, v10
	v_mov_b32_e32 v10, v31
	v_mov_b32_e32 v28, v36
	v_mov_b32_e32 v29, v12
	v_mov_b32_e32 v12, v37
	v_mov_b32_e32 v31, s44
	ds_read_b128 v[34:37], v30
	v_pk_fma_f32 v[78:79], v[178:179], v[100:101], v[82:83] op_sel_hi:[0,1,1]
	v_pk_fma_f32 v[82:83], v[178:179], v[114:115], v[88:89] op_sel_hi:[0,1,1]
	v_pk_fma_f32 v[88:89], v[178:179], v[130:131], v[98:99] op_sel_hi:[0,1,1]
	v_pk_fma_f32 v[98:99], v[178:179], v[42:43], v[40:41] op_sel_hi:[0,1,1]
	v_mov_b32_e32 v24, v16
	v_mov_b32_e32 v25, v0
	v_mov_b32_e32 v0, v17
	v_mov_b32_e32 v16, v18
	v_mov_b32_e32 v17, v2
	v_mov_b32_e32 v2, v19
	v_mov_b32_e32 v18, v22
	v_mov_b32_e32 v19, v6
	v_mov_b32_e32 v6, v23
	v_mov_b32_e32 v22, v38
	v_mov_b32_e32 v23, v14
	v_mov_b32_e32 v14, v39
	ds_read_b128 v[38:41], v31
	s_add_i32 s45, s13, 0xffff3010
	v_pk_fma_f32 v[44:45], v[176:177], v[90:91], v[44:45] op_sel_hi:[0,1,1]
	s_waitcnt lgkmcnt(1)
	v_mov_b32_e32 v30, v34
	s_add_i32 s44, s13, 0xffff2010
	v_mov_b32_e32 v34, s45
	v_pk_fma_f32 v[100:101], v[178:179], v[46:47], v[44:45] op_sel_hi:[0,1,1]
	s_waitcnt lgkmcnt(0)
	v_mov_b32_e32 v31, v38
	v_mov_b32_e32 v38, v35
	v_mov_b32_e32 v46, v36
	v_mov_b32_e32 v47, v40
	v_mov_b32_e32 v40, v37
	v_mov_b32_e32 v42, s44
	ds_read_b128 v[34:37], v34
	ds_read_b128 v[42:45], v42
	s_add_i32 s45, s13, 0xffff5010
	v_pk_fma_f32 v[132:133], v[170:171], v[164:165], v[132:133] op_sel_hi:[0,1,1]
	s_add_i32 s44, s13, 0xffff4010
	s_waitcnt lgkmcnt(1)
	v_mov_b32_e32 v136, v34
	v_mov_b32_e32 v34, s45
	v_pk_fma_f32 v[108:109], v[176:177], v[166:167], v[132:133] op_sel_hi:[0,1,1]
	s_waitcnt lgkmcnt(0)
	v_mov_b32_e32 v137, v42
	v_mov_b32_e32 v42, v35
	v_mov_b32_e32 v138, v36
	v_mov_b32_e32 v139, v44
	v_mov_b32_e32 v44, v37
	v_mov_b32_e32 v103, s44
	ds_read_b128 v[34:37], v34
	v_pk_fma_f32 v[90:91], v[178:179], v[134:135], v[108:109] op_sel_hi:[0,1,1]
	ds_read_b128 v[108:111], v103
	s_add_i32 s45, s13, 0xffff7010
	s_add_i32 s44, s13, 0xffff6010
	s_waitcnt lgkmcnt(1)
	v_mov_b32_e32 v140, v34
	v_mov_b32_e32 v34, s45
	s_waitcnt lgkmcnt(0)
	v_mov_b32_e32 v141, v108
	v_mov_b32_e32 v108, v35
	v_mov_b32_e32 v142, v36
	v_mov_b32_e32 v143, v110
	v_mov_b32_e32 v110, v37
	v_mov_b32_e32 v103, s44
	ds_read_b128 v[34:37], v34
	ds_read_b128 v[112:115], v103
	s_add_i32 s45, s13, 0xffff9010
	s_add_i32 s44, s13, 0xffff8010
	v_mov_b32_e32 v103, s44
	s_waitcnt lgkmcnt(1)
	v_mov_b32_e32 v144, v34
	v_mov_b32_e32 v34, s45
	s_waitcnt lgkmcnt(0)
	v_mov_b32_e32 v145, v112
	v_mov_b32_e32 v112, v35
	v_mov_b32_e32 v146, v36
	v_mov_b32_e32 v147, v114
	v_mov_b32_e32 v114, v37
	ds_read_b128 v[34:37], v34
	ds_read_b128 v[116:119], v103
	s_add_i32 s45, s13, 0xffffb010
	s_add_i32 s44, s13, 0xffffa010
	v_mov_b32_e32 v103, s44
	s_waitcnt lgkmcnt(1)
	v_mov_b32_e32 v148, v34
	v_mov_b32_e32 v34, s45
	s_waitcnt lgkmcnt(0)
	v_mov_b32_e32 v149, v116
	v_mov_b32_e32 v116, v35
	v_mov_b32_e32 v150, v36
	v_mov_b32_e32 v151, v118
	v_mov_b32_e32 v118, v37
	ds_read_b128 v[34:37], v34
	ds_read_b128 v[120:123], v103
	s_add_i32 s45, s13, 0xffffd010
	s_add_i32 s44, s13, 0xffffc010
	v_mov_b32_e32 v103, s44
	s_waitcnt lgkmcnt(1)
	v_mov_b32_e32 v152, v34
	v_mov_b32_e32 v34, s45
	s_waitcnt lgkmcnt(0)
	v_mov_b32_e32 v153, v120
	v_mov_b32_e32 v120, v35
	v_mov_b32_e32 v154, v36
	v_mov_b32_e32 v155, v122
	v_mov_b32_e32 v122, v37
	ds_read_b128 v[34:37], v34
	ds_read_b128 v[128:131], v103
	s_add_i32 s44, s13, 0xffffe010
	s_add_i32 s45, s13, 0xfffff010
	v_mov_b32_e32 v103, s44
	s_waitcnt lgkmcnt(1)
	v_mov_b32_e32 v156, v34
	v_mov_b32_e32 v34, s45
	s_waitcnt lgkmcnt(0)
	v_mov_b32_e32 v157, v128
	v_mov_b32_e32 v128, v35
	v_mov_b32_e32 v158, v36
	v_mov_b32_e32 v159, v130
	v_mov_b32_e32 v130, v37
	ds_read_b128 v[34:37], v34
	ds_read_b128 v[132:135], v103
	v_pk_mul_f32 v[0:1], v[106:107], v[0:1] op_sel_hi:[0,1]
	v_pk_mul_f32 v[4:5], v[106:107], v[4:5] op_sel_hi:[0,1]
	v_pk_fma_f32 v[0:1], v[104:105], v[24:25], v[0:1] op_sel_hi:[0,1,1]
	s_waitcnt lgkmcnt(1)
	v_mov_b32_e32 v160, v34
	s_waitcnt lgkmcnt(0)
	v_mov_b32_e32 v161, v132
	v_mov_b32_e32 v132, v35
	v_mov_b32_e32 v34, v36
	v_mov_b32_e32 v35, v134
	v_mov_b32_e32 v134, v37
	v_pk_mul_f32 v[36:37], v[106:107], v[38:39] op_sel_hi:[0,1]
	v_pk_fma_f32 v[30:31], v[104:105], v[30:31], v[36:37] op_sel_hi:[0,1,1]
	v_pk_mul_f32 v[36:37], v[106:107], v[42:43] op_sel_hi:[0,1]
	v_pk_mul_f32 v[38:39], v[106:107], v[108:109] op_sel_hi:[0,1]
	v_pk_mul_f32 v[42:43], v[106:107], v[112:113] op_sel_hi:[0,1]
	v_pk_mul_f32 v[108:109], v[106:107], v[116:117] op_sel_hi:[0,1]
	v_pk_mul_f32 v[112:113], v[106:107], v[120:121] op_sel_hi:[0,1]
	v_pk_mul_f32 v[120:121], v[106:107], v[132:133] op_sel_hi:[0,1]
	v_pk_fma_f32 v[38:39], v[104:105], v[140:141], v[38:39] op_sel_hi:[0,1,1]
	v_pk_fma_f32 v[108:109], v[104:105], v[148:149], v[108:109] op_sel_hi:[0,1,1]
	v_pk_mul_f32 v[116:117], v[106:107], v[128:129] op_sel_hi:[0,1]
	v_pk_fma_f32 v[120:121], v[104:105], v[160:161], v[120:121] op_sel_hi:[0,1,1]
	v_pk_fma_f32 v[4:5], v[104:105], v[26:27], v[4:5] op_sel_hi:[0,1,1]
	v_pk_mul_f32 v[8:9], v[106:107], v[8:9] op_sel_hi:[0,1]
	v_pk_mul_f32 v[12:13], v[106:107], v[12:13] op_sel_hi:[0,1]
	v_pk_fma_f32 v[116:117], v[104:105], v[156:157], v[116:117] op_sel_hi:[0,1,1]
	v_pk_fma_f32 v[8:9], v[104:105], v[32:33], v[8:9] op_sel_hi:[0,1,1]
	v_pk_fma_f32 v[12:13], v[104:105], v[28:29], v[12:13] op_sel_hi:[0,1,1]
	v_pk_fma_f32 v[28:29], v[102:103], v[142:143], v[38:39] op_sel_hi:[0,1,1]
	v_pk_fma_f32 v[32:33], v[102:103], v[150:151], v[108:109] op_sel_hi:[0,1,1]
	v_pk_fma_f32 v[34:35], v[102:103], v[34:35], v[120:121] op_sel_hi:[0,1,1]
	v_pk_fma_f32 v[0:1], v[102:103], v[16:17], v[0:1] op_sel_hi:[0,1,1]
	v_pk_fma_f32 v[4:5], v[102:103], v[18:19], v[4:5] op_sel_hi:[0,1,1]
	v_pk_fma_f32 v[38:39], v[102:103], v[158:159], v[116:117] op_sel_hi:[0,1,1]
	v_pk_fma_f32 v[106:107], v[124:125], v[110:111], v[28:29] op_sel_hi:[0,1,1]
	v_pk_fma_f32 v[110:111], v[124:125], v[118:119], v[32:33] op_sel_hi:[0,1,1]
	v_pk_fma_f32 v[116:117], v[124:125], v[134:135], v[34:35] op_sel_hi:[0,1,1]
	v_pk_fma_f32 v[118:119], v[124:125], v[2:3], v[0:1] op_sel_hi:[0,1,1]
	v_pk_fma_f32 v[120:121], v[124:125], v[6:7], v[4:5] op_sel_hi:[0,1,1]
	ds_read_b128 v[4:7], v127 offset:4128
	ds_read_b128 v[16:19], v127 offset:4144
	ds_read_b128 v[32:35], v127 offset:32
	ds_read_b128 v[0:3], v127 offset:48
	v_pk_fma_f32 v[36:37], v[104:105], v[136:137], v[36:37] op_sel_hi:[0,1,1]
	v_pk_fma_f32 v[42:43], v[104:105], v[144:145], v[42:43] op_sel_hi:[0,1,1]
	v_pk_fma_f32 v[112:113], v[104:105], v[152:153], v[112:113] op_sel_hi:[0,1,1]
	v_pk_fma_f32 v[24:25], v[102:103], v[46:47], v[30:31] op_sel_hi:[0,1,1]
	v_pk_fma_f32 v[26:27], v[102:103], v[138:139], v[36:37] op_sel_hi:[0,1,1]
	v_pk_fma_f32 v[30:31], v[102:103], v[146:147], v[42:43] op_sel_hi:[0,1,1]
	v_pk_fma_f32 v[36:37], v[102:103], v[154:155], v[112:113] op_sel_hi:[0,1,1]
	v_pk_fma_f32 v[8:9], v[102:103], v[20:21], v[8:9] op_sel_hi:[0,1,1]
	v_pk_fma_f32 v[12:13], v[102:103], v[22:23], v[12:13] op_sel_hi:[0,1,1]
	v_pk_fma_f32 v[108:109], v[124:125], v[114:115], v[30:31] op_sel_hi:[0,1,1]
	v_pk_fma_f32 v[112:113], v[124:125], v[122:123], v[36:37] op_sel_hi:[0,1,1]
	v_pk_fma_f32 v[114:115], v[124:125], v[130:131], v[38:39] op_sel_hi:[0,1,1]
	v_pk_fma_f32 v[122:123], v[124:125], v[10:11], v[8:9] op_sel_hi:[0,1,1]
	s_waitcnt lgkmcnt(3)
	v_mov_b32_e32 v134, v4
	s_waitcnt lgkmcnt(1)
	v_mov_b32_e32 v135, v32
	v_mov_b32_e32 v32, v5
	v_mov_b32_e32 v132, v6
	v_mov_b32_e32 v133, v34
	v_mov_b32_e32 v34, v7
	ds_read_b128 v[8:11], v127 offset:12320
	ds_read_b128 v[20:23], v127 offset:12336
	ds_read_b128 v[36:39], v127 offset:8224
	ds_read_b128 v[4:7], v127 offset:8240
	v_pk_fma_f32 v[102:103], v[124:125], v[40:41], v[24:25] op_sel_hi:[0,1,1]
	v_pk_fma_f32 v[104:105], v[124:125], v[44:45], v[26:27] op_sel_hi:[0,1,1]
	v_pk_fma_f32 v[124:125], v[124:125], v[14:15], v[12:13] op_sel_hi:[0,1,1]
	s_waitcnt lgkmcnt(3)
	v_mov_b32_e32 v138, v8
	s_waitcnt lgkmcnt(1)
	v_mov_b32_e32 v139, v36
	v_mov_b32_e32 v36, v9
	v_mov_b32_e32 v136, v10
	v_mov_b32_e32 v137, v38
	v_mov_b32_e32 v38, v11
	ds_read_b128 v[12:15], v127 offset:20512
	ds_read_b128 v[24:27], v127 offset:20528
	ds_read_b128 v[40:43], v127 offset:16416
	ds_read_b128 v[8:11], v127 offset:16432
	ds_read_b128 v[128:131], v127 offset:28704
	ds_read_b128 v[28:31], v127 offset:28720
	s_add_i32 s45, s13, 0xffff1020
	s_waitcnt lgkmcnt(5)
	v_mov_b32_e32 v146, v12
	s_waitcnt lgkmcnt(3)
	v_mov_b32_e32 v147, v40
	v_mov_b32_e32 v40, v13
	v_mov_b32_e32 v140, v14
	v_mov_b32_e32 v141, v42
	v_mov_b32_e32 v42, v15
	ds_read_b128 v[44:47], v127 offset:24608
	ds_read_b128 v[12:15], v127 offset:24624
	s_waitcnt lgkmcnt(3)
	v_mov_b32_e32 v180, v128
	s_add_i32 s44, s13, 0xffff0020
	v_mov_b32_e32 v128, s45
	s_waitcnt lgkmcnt(1)
	v_mov_b32_e32 v181, v44
	v_mov_b32_e32 v44, v129
	v_mov_b32_e32 v182, v130
	v_mov_b32_e32 v183, v46
	v_mov_b32_e32 v46, v131
	v_mov_b32_e32 v127, s44
	ds_read_b128 v[128:131], v128
	ds_read_b128 v[148:151], v127
	s_add_i32 s45, s13, 0xffff3020
	s_add_i32 s44, s13, 0xffff2020
	v_mov_b32_e32 v127, s44
	s_waitcnt lgkmcnt(1)
	v_mov_b32_e32 v184, v128
	v_mov_b32_e32 v128, s45
	s_waitcnt lgkmcnt(0)
	v_mov_b32_e32 v185, v148
	v_mov_b32_e32 v148, v129
	v_mov_b32_e32 v186, v130
	v_mov_b32_e32 v187, v150
	v_mov_b32_e32 v150, v131
	ds_read_b128 v[128:131], v128
	ds_read_b128 v[152:155], v127
	s_add_i32 s45, s13, 0xffff5020
	s_add_i32 s44, s13, 0xffff4020
	v_mov_b32_e32 v127, s44
	s_waitcnt lgkmcnt(1)
	v_mov_b32_e32 v188, v128
	v_mov_b32_e32 v128, s45
	s_waitcnt lgkmcnt(0)
	v_mov_b32_e32 v189, v152
	v_mov_b32_e32 v152, v129
	v_mov_b32_e32 v190, v130
	v_mov_b32_e32 v191, v154
	v_mov_b32_e32 v154, v131
	ds_read_b128 v[128:131], v128
	ds_read_b128 v[156:159], v127
	s_add_i32 s45, s13, 0xffff7020
	s_add_i32 s44, s13, 0xffff6020
	v_mov_b32_e32 v127, s44
	s_waitcnt lgkmcnt(1)
	v_mov_b32_e32 v192, v128
	v_mov_b32_e32 v128, s45
	s_waitcnt lgkmcnt(0)
	v_mov_b32_e32 v193, v156
	v_mov_b32_e32 v156, v129
	v_mov_b32_e32 v194, v130
	v_mov_b32_e32 v195, v158
	v_mov_b32_e32 v158, v131
	ds_read_b128 v[128:131], v128
	ds_read_b128 v[160:163], v127
	s_add_i32 s45, s13, 0xffff9020
	s_add_i32 s44, s13, 0xffff8020
	v_mov_b32_e32 v127, s44
	s_waitcnt lgkmcnt(1)
	v_mov_b32_e32 v196, v128
	v_mov_b32_e32 v128, s45
	s_waitcnt lgkmcnt(0)
	v_mov_b32_e32 v197, v160
	v_mov_b32_e32 v160, v129
	v_mov_b32_e32 v198, v130
	v_mov_b32_e32 v199, v162
	v_mov_b32_e32 v162, v131
	ds_read_b128 v[128:131], v128
	ds_read_b128 v[164:167], v127
	s_add_i32 s45, s13, 0xffffb020
	s_add_i32 s44, s13, 0xffffa020
	v_mov_b32_e32 v127, s44
	s_waitcnt lgkmcnt(1)
	v_mov_b32_e32 v200, v128
	v_mov_b32_e32 v128, s45
	s_waitcnt lgkmcnt(0)
	v_mov_b32_e32 v201, v164
	v_mov_b32_e32 v164, v129
	v_mov_b32_e32 v202, v130
	v_mov_b32_e32 v203, v166
	v_mov_b32_e32 v166, v131
	ds_read_b128 v[128:131], v128
	ds_read_b128 v[168:171], v127
	s_add_i32 s45, s13, 0xffffd020
	s_add_i32 s44, s13, 0xffffc020
	v_mov_b32_e32 v127, s44
	s_waitcnt lgkmcnt(1)
	v_mov_b32_e32 v204, v128
	v_mov_b32_e32 v128, s45
	s_waitcnt lgkmcnt(0)
	v_mov_b32_e32 v205, v168
	v_mov_b32_e32 v168, v129
	v_mov_b32_e32 v206, v130
	v_mov_b32_e32 v207, v170
	v_mov_b32_e32 v170, v131
	ds_read_b128 v[128:131], v128
	ds_read_b128 v[172:175], v127
	s_add_i32 s45, s13, 0xfffff020
	s_add_i32 s44, s13, 0xffffe020
	v_mov_b32_e32 v127, s44
	s_waitcnt lgkmcnt(1)
	v_mov_b32_e32 v208, v128
	v_mov_b32_e32 v128, s45
	s_waitcnt lgkmcnt(0)
	v_mov_b32_e32 v209, v172
	v_mov_b32_e32 v172, v129
	v_mov_b32_e32 v210, v130
	v_mov_b32_e32 v211, v174
	v_mov_b32_e32 v174, v131
	ds_read_b128 v[128:131], v128
	ds_read_b128 v[176:179], v127
	s_add_i32 s45, s13, 0xffff1030
	s_add_i32 s44, s13, 0xffff0030
	v_pk_add_f32 v[64:65], v[64:65], v[90:91]
	s_waitcnt lgkmcnt(1)
	v_mov_b32_e32 v212, v128
	v_add_co_u32_e32 v128, vcc, s29, v52
	s_waitcnt lgkmcnt(0)
	v_mov_b32_e32 v213, v176
	v_mov_b32_e32 v176, v129
	v_addc_co_u32_e32 v129, vcc, 0, v53, vcc
	v_mov_b32_e32 v214, v130
	v_add_co_u32_e32 v130, vcc, s38, v52
	v_mov_b32_e32 v215, v178
	v_mov_b32_e32 v178, v131
	v_addc_co_u32_e32 v131, vcc, 0, v53, vcc
	v_add_co_u32_e32 v142, vcc, s39, v52
	v_pk_add_f32 v[62:63], v[62:63], v[92:93]
	s_nop 0
	v_addc_co_u32_e32 v143, vcc, 0, v53, vcc
	v_add_co_u32_e32 v144, vcc, s40, v52
	v_pk_add_f32 v[60:61], v[60:61], v[94:95]
	s_nop 0
	v_addc_co_u32_e32 v145, vcc, 0, v53, vcc
	v_add_co_u32_e32 v216, vcc, s41, v52
	v_pk_add_f32 v[58:59], v[58:59], v[96:97]
	s_nop 0
	v_addc_co_u32_e32 v217, vcc, 0, v53, vcc
	v_add_co_u32_e32 v218, vcc, s42, v52
	v_pk_add_f32 v[56:57], v[56:57], v[98:99]
	s_nop 0
	v_addc_co_u32_e32 v219, vcc, 0, v53, vcc
	v_add_co_u32_e32 v220, vcc, s43, v52
	v_pk_add_f32 v[54:55], v[54:55], v[100:101]
	s_nop 0
	v_addc_co_u32_e32 v221, vcc, 0, v53, vcc
	s_cmp_lt_u32 s5, s11
	s_cbranch_scc0 .Lp0_lastB
	s_waitcnt vmcnt(9)
	v_mov_b32_e32 v222, v245
	v_mov_b32_e32 v224, v246
	v_mov_b32_e32 v226, v247
	v_mov_b32_e32 v142, v248
	v_mov_b32_e32 v144, v249
	v_mov_b32_e32 v130, v250
	v_mov_b32_e32 v128, v251
	v_lshl_add_u64 v[228:229], v[234:235], 0, s[100:101]
	global_load_dword v245, v[228:229], off
	v_lshl_add_u64 v[230:231], v[228:229], 0, s[100:101]
	global_load_dword v246, v[230:231], off
	v_lshl_add_u64 v[232:233], v[230:231], 0, s[100:101]
	global_load_dword v247, v[232:233], off
	v_lshl_add_u64 v[228:229], v[232:233], 0, s[100:101]
	global_load_dword v248, v[228:229], off
	v_lshl_add_u64 v[230:231], v[228:229], 0, s[100:101]
	global_load_dword v249, v[230:231], off
	v_lshl_add_u64 v[232:233], v[230:231], 0, s[100:101]
	global_load_dword v250, v[232:233], off
	v_lshl_add_u64 v[228:229], v[232:233], 0, s[100:101]
	global_load_dword v251, v[228:229], off
	s_branch .Lp0_Bdone
.Lp0_lastB:
	s_waitcnt vmcnt(0)
	v_mov_b32_e32 v222, v245
	v_mov_b32_e32 v224, v246
	v_mov_b32_e32 v226, v247
	v_mov_b32_e32 v142, v248
	v_mov_b32_e32 v144, v249
	v_mov_b32_e32 v130, v250
	v_mov_b32_e32 v128, v251
.Lp0_Bdone:
	v_pk_add_f32 v[64:65], v[64:65], v[114:115]
	v_pk_add_f32 v[62:63], v[62:63], v[116:117]
	v_pk_add_f32 v[60:61], v[60:61], v[118:119]
	v_pk_add_f32 v[58:59], v[58:59], v[120:121]
	v_pk_add_f32 v[56:57], v[56:57], v[122:123]
	v_pk_add_f32 v[54:55], v[54:55], v[124:125]
	v_lshl_add_u64 v[52:53], v[52:53], 0, s[8:9]
	v_pk_mul_f32 v[152:153], v[222:223], v[152:153] op_sel_hi:[0,1]
	v_pk_mul_f32 v[168:169], v[222:223], v[168:169] op_sel_hi:[0,1]
	v_pk_mul_f32 v[36:37], v[222:223], v[36:37] op_sel_hi:[0,1]
	v_pk_mul_f32 v[40:41], v[222:223], v[40:41] op_sel_hi:[0,1]
	v_pk_mul_f32 v[44:45], v[222:223], v[44:45] op_sel_hi:[0,1]
	v_pk_mul_f32 v[148:149], v[222:223], v[148:149] op_sel_hi:[0,1]
	v_pk_fma_f32 v[152:153], v[126:127], v[188:189], v[152:153] op_sel_hi:[0,1,1]
	v_pk_mul_f32 v[160:161], v[222:223], v[160:161] op_sel_hi:[0,1]
	v_pk_fma_f32 v[168:169], v[126:127], v[204:205], v[168:169] op_sel_hi:[0,1,1]
	v_pk_mul_f32 v[32:33], v[222:223], v[32:33] op_sel_hi:[0,1]
	v_pk_fma_f32 v[36:37], v[126:127], v[138:139], v[36:37] op_sel_hi:[0,1,1]
	v_pk_fma_f32 v[40:41], v[126:127], v[146:147], v[40:41] op_sel_hi:[0,1,1]
	v_pk_fma_f32 v[44:45], v[126:127], v[180:181], v[44:45] op_sel_hi:[0,1,1]
	v_pk_fma_f32 v[148:149], v[126:127], v[184:185], v[148:149] op_sel_hi:[0,1,1]
	v_pk_mul_f32 v[156:157], v[222:223], v[156:157] op_sel_hi:[0,1]
	v_pk_fma_f32 v[160:161], v[126:127], v[196:197], v[160:161] op_sel_hi:[0,1,1]
	v_pk_mul_f32 v[164:165], v[222:223], v[164:165] op_sel_hi:[0,1]
	v_pk_mul_f32 v[172:173], v[222:223], v[172:173] op_sel_hi:[0,1]
	v_pk_mul_f32 v[176:177], v[222:223], v[176:177] op_sel_hi:[0,1]
	v_pk_fma_f32 v[32:33], v[126:127], v[134:135], v[32:33] op_sel_hi:[0,1,1]
	v_pk_fma_f32 v[134:135], v[224:225], v[190:191], v[152:153] op_sel_hi:[0,1,1]
	v_pk_fma_f32 v[152:153], v[224:225], v[206:207], v[168:169] op_sel_hi:[0,1,1]
	v_pk_fma_f32 v[36:37], v[224:225], v[136:137], v[36:37] op_sel_hi:[0,1,1]
	v_pk_fma_f32 v[40:41], v[224:225], v[140:141], v[40:41] op_sel_hi:[0,1,1]
	v_pk_fma_f32 v[168:169], v[224:225], v[182:183], v[44:45] op_sel_hi:[0,1,1]
	v_pk_fma_f32 v[156:157], v[126:127], v[192:193], v[156:157] op_sel_hi:[0,1,1]
	v_pk_fma_f32 v[164:165], v[126:127], v[200:201], v[164:165] op_sel_hi:[0,1,1]
	v_pk_fma_f32 v[172:173], v[126:127], v[208:209], v[172:173] op_sel_hi:[0,1,1]
	v_pk_fma_f32 v[176:177], v[126:127], v[212:213], v[176:177] op_sel_hi:[0,1,1]
	v_pk_fma_f32 v[126:127], v[224:225], v[186:187], v[148:149] op_sel_hi:[0,1,1]
	v_pk_fma_f32 v[146:147], v[224:225], v[198:199], v[160:161] op_sel_hi:[0,1,1]
	v_pk_fma_f32 v[36:37], v[226:227], v[38:39], v[36:37] op_sel_hi:[0,1,1]
	v_pk_fma_f32 v[38:39], v[226:227], v[42:43], v[40:41] op_sel_hi:[0,1,1]
	v_pk_fma_f32 v[40:41], v[226:227], v[46:47], v[168:169] op_sel_hi:[0,1,1]
	v_mov_b32_e32 v46, v20
	v_mov_b32_e32 v20, v26
	v_mov_b32_e32 v26, s45
	v_pk_fma_f32 v[148:149], v[224:225], v[202:203], v[164:165] op_sel_hi:[0,1,1]
	v_pk_fma_f32 v[44:45], v[226:227], v[150:151], v[126:127] op_sel_hi:[0,1,1]
	v_pk_fma_f32 v[126:127], v[226:227], v[154:155], v[134:135] op_sel_hi:[0,1,1]
	v_pk_fma_f32 v[134:135], v[226:227], v[162:163], v[146:147] op_sel_hi:[0,1,1]
	v_mov_b32_e32 v43, v0
	v_mov_b32_e32 v0, v17
	v_mov_b32_e32 v17, v2
	v_mov_b32_e32 v2, v19
	v_mov_b32_e32 v47, v4
	v_mov_b32_e32 v4, v21
	v_mov_b32_e32 v19, v6
	v_mov_b32_e32 v6, v23
	v_mov_b32_e32 v146, v24
	v_mov_b32_e32 v147, v8
	v_mov_b32_e32 v8, v25
	v_mov_b32_e32 v21, v10
	v_mov_b32_e32 v10, v27
	v_mov_b32_e32 v24, v28
	v_mov_b32_e32 v25, v12
	v_mov_b32_e32 v12, v29
	v_mov_b32_e32 v23, v14
	v_mov_b32_e32 v14, v31
	v_mov_b32_e32 v31, s44
	ds_read_b128 v[26:29], v26
	v_pk_fma_f32 v[136:137], v[226:227], v[166:167], v[148:149] op_sel_hi:[0,1,1]
	ds_read_b128 v[148:151], v31
	s_add_i32 s45, s13, 0xffff3030
	v_mov_b32_e32 v42, v16
	v_mov_b32_e32 v16, v18
	v_mov_b32_e32 v18, v22
	v_mov_b32_e32 v22, v30
	s_waitcnt lgkmcnt(1)
	v_mov_b32_e32 v30, v26
	s_add_i32 s44, s13, 0xffff2030
	v_mov_b32_e32 v26, s45
	v_pk_fma_f32 v[138:139], v[224:225], v[194:195], v[156:157] op_sel_hi:[0,1,1]
	s_waitcnt lgkmcnt(0)
	v_mov_b32_e32 v31, v148
	v_mov_b32_e32 v148, v27
	v_mov_b32_e32 v180, v28
	v_mov_b32_e32 v181, v150
	v_mov_b32_e32 v150, v29
	v_mov_b32_e32 v129, s44
	ds_read_b128 v[26:29], v26
	v_pk_fma_f32 v[164:165], v[224:225], v[132:133], v[32:33] op_sel_hi:[0,1,1]
	v_pk_fma_f32 v[132:133], v[226:227], v[158:159], v[138:139] op_sel_hi:[0,1,1]
	v_pk_fma_f32 v[138:139], v[226:227], v[170:171], v[152:153] op_sel_hi:[0,1,1]
	ds_read_b128 v[152:155], v129
	s_add_i32 s45, s13, 0xffff5030
	s_waitcnt lgkmcnt(1)
	v_mov_b32_e32 v182, v26
	s_add_i32 s44, s13, 0xffff4030
	v_mov_b32_e32 v26, s45
	v_pk_fma_f32 v[156:157], v[224:225], v[210:211], v[172:173] op_sel_hi:[0,1,1]
	s_waitcnt lgkmcnt(0)
	v_mov_b32_e32 v183, v152
	v_mov_b32_e32 v152, v27
	v_mov_b32_e32 v184, v28
	v_mov_b32_e32 v185, v154
	v_mov_b32_e32 v154, v29
	v_mov_b32_e32 v129, s44
	ds_read_b128 v[26:29], v26
	v_pk_fma_f32 v[140:141], v[226:227], v[174:175], v[156:157] op_sel_hi:[0,1,1]
	ds_read_b128 v[156:159], v129
	s_add_i32 s45, s13, 0xffff7030
	s_add_i32 s44, s13, 0xffff6030
	s_waitcnt lgkmcnt(1)
	v_mov_b32_e32 v186, v26
	v_mov_b32_e32 v26, s45
	v_pk_fma_f32 v[160:161], v[224:225], v[214:215], v[176:177] op_sel_hi:[0,1,1]
	s_waitcnt lgkmcnt(0)
	v_mov_b32_e32 v187, v156
	v_mov_b32_e32 v156, v27
	v_mov_b32_e32 v188, v28
	v_mov_b32_e32 v189, v158
	v_mov_b32_e32 v158, v29
	v_mov_b32_e32 v129, s44
	ds_read_b128 v[26:29], v26
	v_pk_fma_f32 v[32:33], v[226:227], v[178:179], v[160:161] op_sel_hi:[0,1,1]
	ds_read_b128 v[160:163], v129
	s_add_i32 s45, s13, 0xffff9030
	s_add_i32 s44, s13, 0xffff8030
	s_waitcnt lgkmcnt(1)
	v_mov_b32_e32 v190, v26
	v_mov_b32_e32 v26, s45
	s_waitcnt lgkmcnt(0)
	v_mov_b32_e32 v191, v160
	v_mov_b32_e32 v160, v27
	v_mov_b32_e32 v192, v28
	v_mov_b32_e32 v193, v162
	v_mov_b32_e32 v162, v29
	v_mov_b32_e32 v129, s44
	ds_read_b128 v[26:29], v26
	v_pk_fma_f32 v[34:35], v[226:227], v[34:35], v[164:165] op_sel_hi:[0,1,1]
	ds_read_b128 v[164:167], v129
	s_add_i32 s45, s13, 0xffffb030
	s_add_i32 s44, s13, 0xffffa030
	s_waitcnt lgkmcnt(1)
	v_mov_b32_e32 v194, v26
	v_mov_b32_e32 v26, s45
	s_waitcnt lgkmcnt(0)
	v_mov_b32_e32 v195, v164
	v_mov_b32_e32 v164, v27
	v_mov_b32_e32 v196, v28
	v_mov_b32_e32 v197, v166
	v_mov_b32_e32 v166, v29
	v_mov_b32_e32 v129, s44
	ds_read_b128 v[26:29], v26
	ds_read_b128 v[168:171], v129
	s_add_i32 s45, s13, 0xffffd030
	s_add_i32 s44, s13, 0xffffc030
	v_mov_b32_e32 v129, s44
	s_waitcnt lgkmcnt(1)
	v_mov_b32_e32 v198, v26
	v_mov_b32_e32 v26, s45
	s_waitcnt lgkmcnt(0)
	v_mov_b32_e32 v199, v168
	v_mov_b32_e32 v168, v27
	v_mov_b32_e32 v200, v28
	v_mov_b32_e32 v201, v170
	v_mov_b32_e32 v170, v29
	ds_read_b128 v[26:29], v26
	ds_read_b128 v[172:175], v129
	s_add_i32 s44, s13, 0xffffe030
	s_add_i32 s45, s13, 0xfffff030
	v_mov_b32_e32 v129, s44
	s_waitcnt lgkmcnt(1)
	v_mov_b32_e32 v202, v26
	v_mov_b32_e32 v26, s45
	s_waitcnt lgkmcnt(0)
	v_mov_b32_e32 v203, v172
	v_mov_b32_e32 v172, v27
	v_mov_b32_e32 v204, v28
	v_mov_b32_e32 v205, v174
	v_mov_b32_e32 v174, v29
	ds_read_b128 v[26:29], v26
	ds_read_b128 v[176:179], v129
	v_pk_mul_f32 v[0:1], v[144:145], v[0:1] op_sel_hi:[0,1]
	v_pk_mul_f32 v[4:5], v[144:145], v[4:5] op_sel_hi:[0,1]
	v_pk_mul_f32 v[8:9], v[144:145], v[8:9] op_sel_hi:[0,1]
	s_waitcnt lgkmcnt(1)
	v_mov_b32_e32 v206, v26
	s_waitcnt lgkmcnt(0)
	v_mov_b32_e32 v207, v176
	v_mov_b32_e32 v176, v27
	v_mov_b32_e32 v26, v28
	v_mov_b32_e32 v27, v178
	v_mov_b32_e32 v178, v29
	v_pk_mul_f32 v[28:29], v[144:145], v[148:149] op_sel_hi:[0,1]
	v_pk_fma_f32 v[28:29], v[142:143], v[30:31], v[28:29] op_sel_hi:[0,1,1]
	v_pk_mul_f32 v[30:31], v[144:145], v[152:153] op_sel_hi:[0,1]
	v_pk_mul_f32 v[148:149], v[144:145], v[156:157] op_sel_hi:[0,1]
	v_pk_mul_f32 v[152:153], v[144:145], v[160:161] op_sel_hi:[0,1]
	v_pk_mul_f32 v[156:157], v[144:145], v[164:165] op_sel_hi:[0,1]
	v_pk_mul_f32 v[12:13], v[144:145], v[12:13] op_sel_hi:[0,1]
	v_pk_fma_f32 v[152:153], v[142:143], v[190:191], v[152:153] op_sel_hi:[0,1,1]
	v_pk_fma_f32 v[156:157], v[142:143], v[194:195], v[156:157] op_sel_hi:[0,1,1]
	v_pk_fma_f32 v[0:1], v[142:143], v[42:43], v[0:1] op_sel_hi:[0,1,1]
	v_pk_fma_f32 v[4:5], v[142:143], v[46:47], v[4:5] op_sel_hi:[0,1,1]
	v_pk_fma_f32 v[8:9], v[142:143], v[146:147], v[8:9] op_sel_hi:[0,1,1]
	v_pk_fma_f32 v[12:13], v[142:143], v[24:25], v[12:13] op_sel_hi:[0,1,1]
	v_pk_mul_f32 v[160:161], v[144:145], v[168:169] op_sel_hi:[0,1]
	v_pk_mul_f32 v[164:165], v[144:145], v[172:173] op_sel_hi:[0,1]
	v_pk_mul_f32 v[168:169], v[144:145], v[176:177] op_sel_hi:[0,1]
	v_pk_fma_f32 v[24:25], v[130:131], v[180:181], v[28:29] op_sel_hi:[0,1,1]
	v_pk_fma_f32 v[42:43], v[130:131], v[192:193], v[152:153] op_sel_hi:[0,1,1]
	v_pk_fma_f32 v[46:47], v[130:131], v[196:197], v[156:157] op_sel_hi:[0,1,1]
	v_pk_fma_f32 v[0:1], v[130:131], v[16:17], v[0:1] op_sel_hi:[0,1,1]
	v_pk_fma_f32 v[4:5], v[130:131], v[18:19], v[4:5] op_sel_hi:[0,1,1]
	v_pk_fma_f32 v[8:9], v[130:131], v[20:21], v[8:9] op_sel_hi:[0,1,1]
	v_pk_fma_f32 v[12:13], v[130:131], v[22:23], v[12:13] op_sel_hi:[0,1,1]
	v_pk_fma_f32 v[30:31], v[142:143], v[182:183], v[30:31] op_sel_hi:[0,1,1]
	v_pk_fma_f32 v[148:149], v[142:143], v[186:187], v[148:149] op_sel_hi:[0,1,1]
	v_pk_fma_f32 v[160:161], v[142:143], v[198:199], v[160:161] op_sel_hi:[0,1,1]
	v_pk_fma_f32 v[164:165], v[142:143], v[202:203], v[164:165] op_sel_hi:[0,1,1]
	v_pk_fma_f32 v[168:169], v[142:143], v[206:207], v[168:169] op_sel_hi:[0,1,1]
	v_pk_fma_f32 v[16:17], v[128:129], v[150:151], v[24:25] op_sel_hi:[0,1,1]
	v_pk_fma_f32 v[22:23], v[128:129], v[162:163], v[42:43] op_sel_hi:[0,1,1]
	v_pk_fma_f32 v[24:25], v[128:129], v[166:167], v[46:47] op_sel_hi:[0,1,1]
	v_pk_fma_f32 v[0:1], v[128:129], v[2:3], v[0:1] op_sel_hi:[0,1,1]
	v_pk_fma_f32 v[2:3], v[128:129], v[6:7], v[4:5] op_sel_hi:[0,1,1]
	v_pk_fma_f32 v[4:5], v[128:129], v[10:11], v[8:9] op_sel_hi:[0,1,1]
	v_pk_fma_f32 v[6:7], v[128:129], v[14:15], v[12:13] op_sel_hi:[0,1,1]
	v_pk_add_f32 v[8:9], v[76:77], v[78:79]
	v_pk_add_f32 v[10:11], v[74:75], v[80:81]
	v_pk_add_f32 v[12:13], v[72:73], v[82:83]
	v_pk_add_f32 v[14:15], v[70:71], v[84:85]
	v_pk_add_f32 v[42:43], v[68:69], v[86:87]
	v_pk_add_f32 v[46:47], v[66:67], v[88:89]
	v_pk_fma_f32 v[28:29], v[130:131], v[184:185], v[30:31] op_sel_hi:[0,1,1]
	v_pk_fma_f32 v[30:31], v[130:131], v[188:189], v[148:149] op_sel_hi:[0,1,1]
	v_pk_fma_f32 v[142:143], v[130:131], v[200:201], v[160:161] op_sel_hi:[0,1,1]
	v_pk_fma_f32 v[144:145], v[130:131], v[204:205], v[164:165] op_sel_hi:[0,1,1]
	v_pk_fma_f32 v[26:27], v[130:131], v[26:27], v[168:169] op_sel_hi:[0,1,1]
	v_pk_add_f32 v[8:9], v[8:9], v[102:103]
	v_pk_add_f32 v[10:11], v[10:11], v[104:105]
	v_pk_add_f32 v[12:13], v[12:13], v[106:107]
	v_pk_add_f32 v[14:15], v[14:15], v[108:109]
	v_pk_add_f32 v[42:43], v[42:43], v[110:111]
	v_pk_add_f32 v[46:47], v[46:47], v[112:113]
	v_pk_fma_f32 v[18:19], v[128:129], v[154:155], v[28:29] op_sel_hi:[0,1,1]
	v_pk_fma_f32 v[20:21], v[128:129], v[158:159], v[30:31] op_sel_hi:[0,1,1]
	v_pk_fma_f32 v[28:29], v[128:129], v[170:171], v[142:143] op_sel_hi:[0,1,1]
	v_pk_fma_f32 v[30:31], v[128:129], v[174:175], v[144:145] op_sel_hi:[0,1,1]
	v_pk_fma_f32 v[26:27], v[128:129], v[178:179], v[26:27] op_sel_hi:[0,1,1]
	v_pk_add_f32 v[8:9], v[8:9], v[44:45]
	v_pk_add_f32 v[10:11], v[10:11], v[126:127]
	v_pk_add_f32 v[12:13], v[12:13], v[132:133]
	v_pk_add_f32 v[14:15], v[14:15], v[134:135]
	v_pk_add_f32 v[42:43], v[42:43], v[136:137]
	v_pk_add_f32 v[44:45], v[46:47], v[138:139]
	v_pk_add_f32 v[46:47], v[64:65], v[140:141]
	s_add_i32 s13, s13, 64
	v_pk_add_f32 v[32:33], v[62:63], v[32:33]
	v_pk_add_f32 v[34:35], v[60:61], v[34:35]
	v_pk_add_f32 v[36:37], v[58:59], v[36:37]
	v_pk_add_f32 v[38:39], v[56:57], v[38:39]
	v_pk_add_f32 v[40:41], v[54:55], v[40:41]
	s_cmp_lt_u32 s5, s11
	v_pk_add_f32 v[76:77], v[8:9], v[16:17]
	v_pk_add_f32 v[74:75], v[10:11], v[18:19]
	v_pk_add_f32 v[72:73], v[12:13], v[20:21]
	v_pk_add_f32 v[70:71], v[14:15], v[22:23]
	v_pk_add_f32 v[68:69], v[42:43], v[24:25]
	v_pk_add_f32 v[66:67], v[44:45], v[28:29]
	v_pk_add_f32 v[64:65], v[46:47], v[30:31]
	v_pk_add_f32 v[62:63], v[32:33], v[26:27]
	v_pk_add_f32 v[60:61], v[34:35], v[0:1]
	v_pk_add_f32 v[58:59], v[36:37], v[2:3]
	v_pk_add_f32 v[56:57], v[38:39], v[4:5]
	v_pk_add_f32 v[54:55], v[40:41], v[6:7]
	s_cbranch_scc1 .LBB0_12
	s_add_i32 s8, 0, 0x18000
	s_mul_i32 s5, s3, 0x1800
	s_add_i32 s5, s5, s8
	v_add_u32_e32 v2, s5, v50
	s_mul_i32 s5, s10, 0x1800
	s_add_i32 s5, s5, s4
	s_mul_i32 s4, s10, 0x90000
	ds_write2st64_b32 v2, v77, v76 offset1:1
	ds_write2st64_b32 v2, v75, v74 offset0:2 offset1:3
	ds_write2st64_b32 v2, v73, v72 offset0:4 offset1:5
	ds_write2st64_b32 v2, v71, v70 offset0:6 offset1:7
	ds_write2st64_b32 v2, v69, v68 offset0:8 offset1:9
	ds_write2st64_b32 v2, v67, v66 offset0:10 offset1:11
	ds_write2st64_b32 v2, v65, v64 offset0:12 offset1:13
	ds_write2st64_b32 v2, v63, v62 offset0:14 offset1:15
	ds_write2st64_b32 v2, v61, v60 offset0:16 offset1:17
	ds_write2st64_b32 v2, v59, v58 offset0:18 offset1:19
	ds_write2st64_b32 v2, v57, v56 offset0:20 offset1:21
	ds_write2st64_b32 v2, v55, v54 offset0:22 offset1:23
	v_or_b32_e32 v2, s5, v49
	s_mul_hi_i32 s5, s10, 0x90000
	s_add_u32 s4, s6, s4
	v_mov_b32_e32 v0, s30
	v_mov_b32_e32 v1, s31
	v_ashrrev_i32_e32 v3, 31, v2
	s_addc_u32 s5, s7, s5
	v_lshl_add_u64 v[0:1], v[2:3], 2, v[0:1]
	v_lshrrev_b32_e32 v4, 6, v48
	s_movk_i32 s6, 0x6000
	v_mov_b64_e32 v[2:3], s[4:5]
	v_mad_u64_u32 v[2:3], s[4:5], v4, s6, v[2:3]
	v_lshl_add_u64 v[2:3], v[2:3], 0, v[50:51]
	v_lshl_add_u64 v[2:3], s[26:27], 0, v[2:3]
	s_mov_b64 s[4:5], 0x100000
	v_lshl_add_u64 v[2:3], v[2:3], 0, s[4:5]
	v_lshlrev_b32_e32 v4, 2, v48
	s_movk_i32 s4, 0xff00
	v_and_or_b32 v4, v4, s4, v50
	v_add_u32_e32 v4, s8, v4
	v_add_u32_e32 v5, 0xfffffe00, v48
	s_mov_b64 s[4:5], 0
	s_mov_b64 s[6:7], 0x30000
	s_movk_i32 s8, 0x3ff
	s_waitcnt lgkmcnt(0)
	s_barrier
